# mLSTM prefix loop and attention bias: v_pk_fma_f32 replaced by scalar v_fmac/v_fma (same fused math)
# speedup vs baseline: 1.0008x; 1.0008x over previous
; #define LAS __attribute__((address_space(3)))
; __device__ __forceinline__ void attn_mfma_item(const bf16* u, bf16* y, const float* cl, const float* tot, LAS unsigned char* wl, int item, int lane) {
;     ...
; #pragma unroll
;             for (int g = 0; g < 4; ++g) { const f32x4 ncs = *(LAS const f32x4*)(gl + 8 * g + 4 * hi);
; #pragma unroll
;                 for (int e = 0; e < 4; ++e) P[4 * g + e] = fmaf(SC2, Sx[4 * g + e], ncs[e]); }
;             if (diag) {
; #pragma unroll
;                 for (int i = 0; i < 16; ++i) { const int sl = 8 * (i >> 2) + 4 * hi + (i & 3); if (sl > r) P[i] = -1e30f; } }
.LBB0_759:
	s_and_b64 vcc, exec, s[70:71]
	s_cbranch_vccz .LBB0_768
	ds_read_b128 v[52:55], v188 offset:4704
	ds_read_b128 v[56:59], v188 offset:4672
	ds_read_b128 v[60:63], v188 offset:4640
	ds_read_b128 v[64:67], v188 offset:4608
	s_mov_b32 s70, 0x3e38aa3b
	s_waitcnt lgkmcnt(3)
	s_nop 0
	v_fma_f32 v50, v50, s70, v54
	v_fma_f32 v51, v51, s70, v55
	s_waitcnt lgkmcnt(2)
	v_fma_f32 v46, v46, s70, v58
	v_fma_f32 v47, v47, s70, v59
	s_waitcnt lgkmcnt(1)
	v_fma_f32 v42, v42, s70, v62
	v_fma_f32 v43, v43, s70, v63
	s_waitcnt lgkmcnt(0)
	v_fma_f32 v54, v38, s70, v66
	v_fma_f32 v55, v39, s70, v67
	v_fma_f32 v38, v48, s70, v52
	v_fma_f32 v39, v49, s70, v53
	v_fma_f32 v44, v44, s70, v56
	v_fma_f32 v45, v45, s70, v57
	v_fma_f32 v40, v40, s70, v60
	v_fma_f32 v41, v41, s70, v61
	s_and_b64 vcc, exec, s[94:95]
	v_fma_f32 v36, v36, s70, v64
	v_fma_f32 v37, v37, s70, v65
	s_cbranch_vccnz .LBB0_762
	v_readlane_b32 s16, v254, 59
	v_readlane_b32 s17, v254, 60
	v_cndmask_b32_e64 v1, v36, v216, s[20:21]
	v_cndmask_b32_e64 v37, v216, v37, s[18:19]
	v_cndmask_b32_e64 v41, v41, v216, s[16:17]
	v_readlane_b32 s16, v254, 57
	v_readlane_b32 s17, v254, 58
	v_cndmask_b32_e64 v36, v1, v36, s[18:19]
	v_cndmask_b32_e64 v54, v54, v216, s[22:23]
	v_cndmask_b32_e64 v42, v42, v216, s[16:17]
	v_readlane_b32 s16, v254, 55
	v_readlane_b32 s17, v254, 56
	v_cndmask_b32_e64 v55, v55, v216, s[24:25]
	v_cndmask_b32_e64 v40, v40, v216, s[26:27]
	v_cndmask_b32_e64 v43, v43, v216, s[16:17]
	v_readlane_b32 s16, v254, 53
	v_readlane_b32 s17, v254, 54
	v_cndmask_b32_e64 v39, v39, v216, s[30:31]
	v_cndmask_b32_e64 v50, v50, v216, s[28:29]
	v_cndmask_b32_e64 v44, v44, v216, s[16:17]
	v_readlane_b32 s16, v254, 51
	v_readlane_b32 s17, v254, 52
	s_nop 1
	v_cndmask_b32_e64 v45, v45, v216, s[16:17]
	v_readlane_b32 s16, v254, 49
	v_readlane_b32 s17, v254, 50
	s_nop 1
	v_cndmask_b32_e64 v46, v46, v216, s[16:17]
	v_readlane_b32 s16, v254, 47
	v_readlane_b32 s17, v254, 48
	s_nop 1
	v_cndmask_b32_e64 v47, v47, v216, s[16:17]
	v_readlane_b32 s16, v254, 45
	v_readlane_b32 s17, v254, 46
	s_nop 1
	v_cndmask_b32_e64 v38, v38, v216, s[16:17]
	v_readlane_b32 s16, v254, 30
	v_readlane_b32 s17, v254, 31
	s_nop 1
	v_cndmask_b32_e64 v51, v51, v216, s[16:17]

; template <bool OUT>
; __device__ __forceinline__ void mlstm_item(const bf16* u, bf16* y, float* scratch, const float* convw, const float* ib, const float* fbias, const float* normw, LAS unsigned char* wl, int bh, int c, int lane) {
;     ...
;             const float* s0 = scratch + (size_t)(bh * 16 + cp) * ML_ITEM_F;
;             f32x16 v0[4];
; #pragma unroll
;             for (int blk = 0; blk < 4; ++blk) v0[blk] = *(const f32x16*)(s0 + blk * 1024 + lane * 16);
;             const float n0 = s0[4096 + lane], g0 = s0[4160];
; #pragma unroll
;             for (int blk = 0; blk < 4; ++blk) X[blk >> 1][blk & 1] += v0[blk] * dec;
;             nk += dec * n0;
;             dec *= __expf(g0);
;         }
.LBB0_784:
	s_add_i32 s0, s3, s53
	s_add_i32 s0, s0, -2
	s_mul_hi_u32 s1, s0, 0x4200
	s_mulk_i32 s0, 0x4200
	s_add_u32 s0, s60, s0
	s_addc_u32 s1, s61, s1
	v_lshl_add_u64 v[84:85], v[142:143], 2, s[0:1]
	s_mov_b64 s[54:55], 0x1000
	v_lshl_add_u64 v[88:89], v[84:85], 0, s[54:55]
	v_add_co_u32_e32 v90, vcc, s83, v84
	s_mov_b64 s[54:55], 0x2000
	s_nop 0
	v_addc_co_u32_e32 v91, vcc, 0, v85, vcc
	v_lshl_add_u64 v[92:93], v[84:85], 0, s[54:55]
	s_mov_b64 s[54:55], 0x3000
	global_load_dwordx4 v[68:71], v[84:85], off
	global_load_dwordx4 v[72:75], v[84:85], off offset:16
	global_load_dwordx4 v[76:79], v[84:85], off offset:32
	global_load_dwordx4 v[80:83], v[84:85], off offset:48
	v_lshl_add_u64 v[132:133], v[84:85], 0, s[54:55]
	v_add_co_u32_e32 v84, vcc, s56, v84
	v_lshl_add_u64 v[86:87], v[202:203], 2, s[0:1]
	s_nop 0
	v_addc_co_u32_e32 v85, vcc, 0, v85, vcc
	v_add_co_u32_e32 v86, vcc, s88, v86
	s_add_i32 s53, s53, -1
	s_nop 0
	v_addc_co_u32_e32 v87, vcc, 0, v87, vcc
	global_load_dwordx4 v[116:119], v[90:91], off offset:-4096
	global_load_dwordx4 v[128:131], v[88:89], off offset:48
	global_load_dwordx4 v[124:127], v[88:89], off offset:32
	global_load_dwordx4 v[120:123], v[88:89], off offset:16
	global_load_dwordx4 v[100:103], v[90:91], off
	global_load_dwordx4 v[112:115], v[92:93], off offset:48
	global_load_dwordx4 v[108:111], v[92:93], off offset:32
	global_load_dwordx4 v[104:107], v[92:93], off offset:16
	s_nop 0
	global_load_dwordx4 v[92:95], v[84:85], off
	global_load_dwordx4 v[96:99], v[132:133], off offset:48
	global_load_dword v134, v[86:87], off
	global_load_dword v135, v209, s[0:1] offset:256
	global_load_dwordx4 v[88:91], v[132:133], off offset:32
	s_nop 0
	global_load_dwordx4 v[84:87], v[132:133], off offset:16
	s_cmp_lt_u32 s53, 2
	s_waitcnt vmcnt(17)
	v_fmac_f32_e32 v4, v68, v2
	v_fmac_f32_e32 v5, v69, v2
	s_waitcnt vmcnt(16)
	v_fmac_f32_e32 v10, v74, v2
	v_fmac_f32_e32 v11, v75, v2
	s_waitcnt vmcnt(15)
	v_fmac_f32_e32 v14, v78, v2
	v_fmac_f32_e32 v15, v79, v2
	s_waitcnt vmcnt(14)
	v_fmac_f32_e32 v18, v82, v2
	v_fmac_f32_e32 v19, v83, v2
	v_fmac_f32_e32 v6, v70, v2
	v_fmac_f32_e32 v7, v71, v2
	v_fmac_f32_e32 v16, v80, v2
	v_fmac_f32_e32 v17, v81, v2
	v_fmac_f32_e32 v12, v76, v2
	v_fmac_f32_e32 v13, v77, v2
	v_fmac_f32_e32 v8, v72, v2
	v_fmac_f32_e32 v9, v73, v2
	s_waitcnt vmcnt(13)
	v_fmac_f32_e32 v22, v2, v118
	v_fmac_f32_e32 v23, v2, v119
	s_waitcnt vmcnt(12)
	v_fmac_f32_e32 v34, v2, v130
	v_fmac_f32_e32 v35, v2, v131
	s_waitcnt vmcnt(11)
	v_fmac_f32_e32 v30, v2, v126
	v_fmac_f32_e32 v31, v2, v127
	s_waitcnt vmcnt(10)
	v_fmac_f32_e32 v26, v2, v122
	v_fmac_f32_e32 v27, v2, v123
	v_fmac_f32_e32 v20, v2, v116
	v_fmac_f32_e32 v21, v2, v117
	s_waitcnt vmcnt(2)
	v_mul_f32_e32 v68, 0x3fb8aa3b, v135
	v_exp_f32_e32 v68, v68
	v_fmac_f32_e32 v32, v2, v128
	v_fmac_f32_e32 v33, v2, v129
	v_fmac_f32_e32 v28, v2, v124
	v_fmac_f32_e32 v29, v2, v125
	v_fmac_f32_e32 v24, v2, v120
	v_fmac_f32_e32 v25, v2, v121
	v_fmac_f32_e32 v38, v2, v102
	v_fmac_f32_e32 v39, v2, v103
	v_fmac_f32_e32 v50, v2, v114
	v_fmac_f32_e32 v51, v2, v115
	v_fmac_f32_e32 v46, v2, v110
	v_fmac_f32_e32 v47, v2, v111
	v_fmac_f32_e32 v42, v2, v106
	v_fmac_f32_e32 v43, v2, v107
	v_fmac_f32_e32 v36, v2, v100
	v_fmac_f32_e32 v37, v2, v101
	v_fmac_f32_e32 v48, v2, v112
	v_fmac_f32_e32 v49, v2, v113
	v_fmac_f32_e32 v44, v2, v108
	v_fmac_f32_e32 v45, v2, v109
	v_fmac_f32_e32 v40, v2, v104
	v_fmac_f32_e32 v41, v2, v105
	v_fmac_f32_e32 v54, v2, v94
	v_fmac_f32_e32 v55, v2, v95
	v_fmac_f32_e32 v66, v2, v98
	v_fmac_f32_e32 v67, v2, v99
	s_waitcnt vmcnt(1)
	v_fmac_f32_e32 v62, v2, v90
	v_fmac_f32_e32 v63, v2, v91
	s_waitcnt vmcnt(0)
	v_fmac_f32_e32 v58, v2, v86
	v_fmac_f32_e32 v59, v2, v87
	v_fmac_f32_e32 v52, v2, v92
	v_fmac_f32_e32 v53, v2, v93
	v_fmac_f32_e32 v64, v2, v96
	v_fmac_f32_e32 v65, v2, v97
	v_fmac_f32_e32 v60, v2, v88
	v_fmac_f32_e32 v61, v2, v89
	v_fmac_f32_e32 v56, v2, v84
	v_fmac_f32_e32 v57, v2, v85
	v_fmac_f32_e32 v226, v2, v134
	v_mul_f32_e32 v2, v2, v68
	s_cbranch_scc0 .LBB0_784
	s_branch .LBB0_786
